# th13 with the exit branch moved two MFMAs before the segment end (exit path re-issues them) so no instruction sits between the last MFMA and the barrier
# baseline (speedup 1.0000x reference)
.LBB0_256:
	s_add_u32 s22, s2, 0xfff80800
	s_addc_u32 s23, s3, -1
	s_add_i32 s48, 0, 0x10000
	s_cmp_eq_u32 s35, 28
	s_cselect_b32 s27, s8, s23
	s_cselect_b32 s26, s9, s22
	s_cselect_b32 s23, s15, s34
	s_cselect_b32 s22, s17, s33
	s_add_i32 s50, 0, 0x14000
	v_add_u32_e32 v176, s48, v191
	v_add_u32_e32 v188, s50, v191
	ds_read_b128 v[148:151], v176
	ds_read_b128 v[152:155], v176 offset:1024
	ds_read_b128 v[172:175], v176 offset:2048
	ds_read_b128 v[176:179], v176 offset:3072
	ds_read_b128 v[180:183], v188
	ds_read_b128 v[184:187], v188 offset:1024
	ds_read_b128 v[196:199], v188 offset:2048
	ds_read_b128 v[200:203], v188 offset:3072
	s_add_i32 m0, s39, 0xc000
	ds_read_b128 v[204:207], v194
	ds_read_b128 v[212:215], v194 offset:1024
	ds_read_b128 v[216:219], v194 offset:2048
	ds_read_b128 v[220:223], v194 offset:3072
	ds_read_b128 v[224:227], v194 offset:4096
	ds_read_b128 v[228:231], v194 offset:5120
	ds_read_b128 v[232:235], v194 offset:6144
	ds_read_b128 v[236:239], v194 offset:7168
	global_load_lds_dwordx4 v168, s[2:3]
	s_add_i32 m0, s39, 0xe000
	s_nop 0
	global_load_lds_dwordx4 v170, s[2:3]
	s_waitcnt vmcnt(8)
	s_waitcnt lgkmcnt(0)
	s_setprio 1
	s_barrier
	v_mfma_f32_16x16x32_bf16 v[144:147], v[148:151], v[204:207], v[144:147]
	v_mfma_f32_16x16x32_bf16 v[136:139], v[172:175], v[204:207], v[136:139]
	v_mfma_f32_16x16x32_bf16 v[128:131], v[148:151], v[216:219], v[128:131]
	v_mfma_f32_16x16x32_bf16 v[120:123], v[172:175], v[216:219], v[120:123]
	v_mfma_f32_16x16x32_bf16 v[112:115], v[148:151], v[224:227], v[112:115]
	v_mfma_f32_16x16x32_bf16 v[104:107], v[172:175], v[224:227], v[104:107]
	v_mfma_f32_16x16x32_bf16 v[96:99], v[148:151], v[232:235], v[96:99]
	v_mfma_f32_16x16x32_bf16 v[88:91], v[172:175], v[232:235], v[88:91]
	v_mfma_f32_16x16x32_bf16 v[144:147], v[152:155], v[212:215], v[144:147]
	v_mfma_f32_16x16x32_bf16 v[136:139], v[176:179], v[212:215], v[136:139]
	v_mfma_f32_16x16x32_bf16 v[128:131], v[152:155], v[220:223], v[128:131]
	v_mfma_f32_16x16x32_bf16 v[120:123], v[176:179], v[220:223], v[120:123]
	v_mfma_f32_16x16x32_bf16 v[112:115], v[152:155], v[228:231], v[112:115]
	v_mfma_f32_16x16x32_bf16 v[104:107], v[176:179], v[228:231], v[104:107]
	v_mfma_f32_16x16x32_bf16 v[96:99], v[152:155], v[236:239], v[96:99]
	v_mfma_f32_16x16x32_bf16 v[88:91], v[176:179], v[236:239], v[88:91]
	v_mfma_f32_16x16x32_bf16 v[140:143], v[180:183], v[204:207], v[140:143]
	v_mfma_f32_16x16x32_bf16 v[132:135], v[196:199], v[204:207], v[132:135]
	v_mfma_f32_16x16x32_bf16 v[124:127], v[180:183], v[216:219], v[124:127]
	v_mfma_f32_16x16x32_bf16 v[116:119], v[196:199], v[216:219], v[116:119]
	v_mfma_f32_16x16x32_bf16 v[108:111], v[180:183], v[224:227], v[108:111]
	v_mfma_f32_16x16x32_bf16 v[100:103], v[196:199], v[224:227], v[100:103]
	v_mfma_f32_16x16x32_bf16 v[92:95], v[180:183], v[232:235], v[92:95]
	v_mfma_f32_16x16x32_bf16 v[84:87], v[196:199], v[232:235], v[84:87]
	v_mfma_f32_16x16x32_bf16 v[140:143], v[184:187], v[212:215], v[140:143]
	v_mfma_f32_16x16x32_bf16 v[132:135], v[200:203], v[212:215], v[132:135]
	v_mfma_f32_16x16x32_bf16 v[124:127], v[184:187], v[220:223], v[124:127]
	v_mfma_f32_16x16x32_bf16 v[116:119], v[200:203], v[220:223], v[116:119]
	v_mfma_f32_16x16x32_bf16 v[108:111], v[184:187], v[228:231], v[108:111]
	v_mfma_f32_16x16x32_bf16 v[100:103], v[200:203], v[228:231], v[100:103]
	v_mfma_f32_16x16x32_bf16 v[92:95], v[184:187], v[236:239], v[92:95]
	v_mfma_f32_16x16x32_bf16 v[84:87], v[200:203], v[236:239], v[84:87]
	s_barrier
	s_setprio 0
	s_add_i32 s48, s48, s28
	s_add_u32 s98, s22, 0x80
	s_addc_u32 s99, s23, 0
	s_add_u32 s100, s26, 0x800
	s_addc_u32 s101, s27, 0
	s_mov_b32 m0, s48
	ds_read_b128 v[204:207], v194 offset:16384
	ds_read_b128 v[212:215], v194 offset:17408
	ds_read_b128 v[216:219], v194 offset:18432
	ds_read_b128 v[220:223], v194 offset:19456
	ds_read_b128 v[224:227], v194 offset:20480
	ds_read_b128 v[228:231], v194 offset:21504
	ds_read_b128 v[232:235], v194 offset:22528
	ds_read_b128 v[236:239], v194 offset:23552
	global_load_lds_dwordx4 v2, s[22:23]
	s_add_i32 m0, s48, 0x2000
	s_add_u32 s48, s22, 0x80000
	s_addc_u32 s49, s23, 0
	s_add_i32 s50, s50, s28
	global_load_lds_dwordx4 v156, s[22:23]
	s_mov_b32 m0, s50
	s_nop 0
	global_load_lds_dwordx4 v2, s[48:49]
	s_add_i32 m0, s50, 0x2000
	s_nop 0
	global_load_lds_dwordx4 v156, s[48:49]
	s_mov_b32 m0, s39
	s_nop 0
	global_load_lds_dwordx4 v160, s[26:27]
	s_mov_b32 m0, s41
	s_nop 0
	global_load_lds_dwordx4 v158, s[26:27]
	s_waitcnt vmcnt(8)
	s_waitcnt lgkmcnt(0)
	s_setprio 1
	s_barrier
	v_mfma_f32_16x16x32_bf16 v[80:83], v[148:151], v[204:207], v[80:83]
	v_mfma_f32_16x16x32_bf16 v[72:75], v[172:175], v[204:207], v[72:75]
	v_mfma_f32_16x16x32_bf16 v[64:67], v[148:151], v[216:219], v[64:67]
	v_mfma_f32_16x16x32_bf16 v[56:59], v[172:175], v[216:219], v[56:59]
	v_mfma_f32_16x16x32_bf16 v[48:51], v[148:151], v[224:227], v[48:51]
	v_mfma_f32_16x16x32_bf16 v[40:43], v[172:175], v[224:227], v[40:43]
	v_mfma_f32_16x16x32_bf16 v[32:35], v[148:151], v[232:235], v[32:35]
	v_mfma_f32_16x16x32_bf16 v[24:27], v[172:175], v[232:235], v[24:27]
	v_mfma_f32_16x16x32_bf16 v[80:83], v[152:155], v[212:215], v[80:83]
	v_mfma_f32_16x16x32_bf16 v[72:75], v[176:179], v[212:215], v[72:75]
	v_mfma_f32_16x16x32_bf16 v[64:67], v[152:155], v[220:223], v[64:67]
	v_mfma_f32_16x16x32_bf16 v[56:59], v[176:179], v[220:223], v[56:59]
	v_mfma_f32_16x16x32_bf16 v[48:51], v[152:155], v[228:231], v[48:51]
	v_mfma_f32_16x16x32_bf16 v[40:43], v[176:179], v[228:231], v[40:43]
	v_mfma_f32_16x16x32_bf16 v[32:35], v[152:155], v[236:239], v[32:35]
	v_mfma_f32_16x16x32_bf16 v[24:27], v[176:179], v[236:239], v[24:27]
	v_mfma_f32_16x16x32_bf16 v[76:79], v[180:183], v[204:207], v[76:79]
	v_mfma_f32_16x16x32_bf16 v[68:71], v[196:199], v[204:207], v[68:71]
	v_mfma_f32_16x16x32_bf16 v[60:63], v[180:183], v[216:219], v[60:63]
	v_mfma_f32_16x16x32_bf16 v[52:55], v[196:199], v[216:219], v[52:55]
	v_mfma_f32_16x16x32_bf16 v[44:47], v[180:183], v[224:227], v[44:47]
	v_mfma_f32_16x16x32_bf16 v[36:39], v[196:199], v[224:227], v[36:39]
	v_mfma_f32_16x16x32_bf16 v[28:31], v[180:183], v[232:235], v[28:31]
	v_mfma_f32_16x16x32_bf16 v[20:23], v[196:199], v[232:235], v[20:23]
	v_mfma_f32_16x16x32_bf16 v[76:79], v[184:187], v[212:215], v[76:79]
	v_mfma_f32_16x16x32_bf16 v[68:71], v[200:203], v[212:215], v[68:71]
	v_mfma_f32_16x16x32_bf16 v[60:63], v[184:187], v[220:223], v[60:63]
	v_mfma_f32_16x16x32_bf16 v[52:55], v[200:203], v[220:223], v[52:55]
	v_mfma_f32_16x16x32_bf16 v[44:47], v[184:187], v[228:231], v[44:47]
	v_mfma_f32_16x16x32_bf16 v[36:39], v[200:203], v[228:231], v[36:39]
	v_mfma_f32_16x16x32_bf16 v[28:31], v[184:187], v[236:239], v[28:31]
	v_mfma_f32_16x16x32_bf16 v[20:23], v[200:203], v[236:239], v[20:23]
	s_barrier
	s_setprio 0
	s_add_i32 s48, 0, 0x18000
	s_add_i32 s49, 0, 0x1c000
	v_add_u32_e32 v176, s48, v191
	v_add_u32_e32 v195, s49, v191
	ds_read_b128 v[148:151], v176
	ds_read_b128 v[152:155], v176 offset:1024
	ds_read_b128 v[172:175], v176 offset:2048
	ds_read_b128 v[176:179], v176 offset:3072
	ds_read_b128 v[180:183], v195
	ds_read_b128 v[184:187], v195 offset:1024
	ds_read_b128 v[196:199], v195 offset:2048
	ds_read_b128 v[200:203], v195 offset:3072
	s_add_u32 s26, s26, 0x80000
	s_addc_u32 s27, s27, 0
	s_mov_b32 m0, s42
	ds_read_b128 v[204:207], v194 offset:32768
	ds_read_b128 v[212:215], v194 offset:33792
	ds_read_b128 v[216:219], v194 offset:34816
	ds_read_b128 v[220:223], v194 offset:35840
	ds_read_b128 v[224:227], v194 offset:36864
	ds_read_b128 v[228:231], v194 offset:37888
	ds_read_b128 v[232:235], v194 offset:38912
	ds_read_b128 v[236:239], v194 offset:39936
	global_load_lds_dwordx4 v160, s[26:27]
	s_mov_b32 m0, s43
	s_nop 0
	global_load_lds_dwordx4 v158, s[26:27]
	s_waitcnt vmcnt(8)
	s_waitcnt lgkmcnt(0)
	s_setprio 1
	s_barrier
	v_mfma_f32_16x16x32_bf16 v[144:147], v[148:151], v[204:207], v[144:147]
	v_mfma_f32_16x16x32_bf16 v[136:139], v[172:175], v[204:207], v[136:139]
	v_mfma_f32_16x16x32_bf16 v[128:131], v[148:151], v[216:219], v[128:131]
	v_mfma_f32_16x16x32_bf16 v[120:123], v[172:175], v[216:219], v[120:123]
	v_mfma_f32_16x16x32_bf16 v[112:115], v[148:151], v[224:227], v[112:115]
	v_mfma_f32_16x16x32_bf16 v[104:107], v[172:175], v[224:227], v[104:107]
	v_mfma_f32_16x16x32_bf16 v[96:99], v[148:151], v[232:235], v[96:99]
	v_mfma_f32_16x16x32_bf16 v[88:91], v[172:175], v[232:235], v[88:91]
	v_mfma_f32_16x16x32_bf16 v[144:147], v[152:155], v[212:215], v[144:147]
	v_mfma_f32_16x16x32_bf16 v[136:139], v[176:179], v[212:215], v[136:139]
	v_mfma_f32_16x16x32_bf16 v[128:131], v[152:155], v[220:223], v[128:131]
	v_mfma_f32_16x16x32_bf16 v[120:123], v[176:179], v[220:223], v[120:123]
	v_mfma_f32_16x16x32_bf16 v[112:115], v[152:155], v[228:231], v[112:115]
	v_mfma_f32_16x16x32_bf16 v[104:107], v[176:179], v[228:231], v[104:107]
	v_mfma_f32_16x16x32_bf16 v[96:99], v[152:155], v[236:239], v[96:99]
	v_mfma_f32_16x16x32_bf16 v[88:91], v[176:179], v[236:239], v[88:91]
	v_mfma_f32_16x16x32_bf16 v[140:143], v[180:183], v[204:207], v[140:143]
	v_mfma_f32_16x16x32_bf16 v[132:135], v[196:199], v[204:207], v[132:135]
	v_mfma_f32_16x16x32_bf16 v[124:127], v[180:183], v[216:219], v[124:127]
	v_mfma_f32_16x16x32_bf16 v[116:119], v[196:199], v[216:219], v[116:119]
	v_mfma_f32_16x16x32_bf16 v[108:111], v[180:183], v[224:227], v[108:111]
	v_mfma_f32_16x16x32_bf16 v[100:103], v[196:199], v[224:227], v[100:103]
	v_mfma_f32_16x16x32_bf16 v[92:95], v[180:183], v[232:235], v[92:95]
	v_mfma_f32_16x16x32_bf16 v[84:87], v[196:199], v[232:235], v[84:87]
	v_mfma_f32_16x16x32_bf16 v[140:143], v[184:187], v[212:215], v[140:143]
	v_mfma_f32_16x16x32_bf16 v[132:135], v[200:203], v[212:215], v[132:135]
	v_mfma_f32_16x16x32_bf16 v[124:127], v[184:187], v[220:223], v[124:127]
	v_mfma_f32_16x16x32_bf16 v[116:119], v[200:203], v[220:223], v[116:119]
	v_mfma_f32_16x16x32_bf16 v[108:111], v[184:187], v[228:231], v[108:111]
	v_mfma_f32_16x16x32_bf16 v[100:103], v[200:203], v[228:231], v[100:103]
	v_mfma_f32_16x16x32_bf16 v[92:95], v[184:187], v[236:239], v[92:95]
	v_mfma_f32_16x16x32_bf16 v[84:87], v[200:203], v[236:239], v[84:87]
	s_barrier
	s_setprio 0
	s_add_i32 s26, s48, s28
	s_mov_b32 m0, s26
	ds_read_b128 v[204:207], v194 offset:49152
	ds_read_b128 v[212:215], v194 offset:50176
	ds_read_b128 v[216:219], v194 offset:51200
	ds_read_b128 v[220:223], v194 offset:52224
	ds_read_b128 v[224:227], v194 offset:53248
	ds_read_b128 v[228:231], v194 offset:54272
	ds_read_b128 v[232:235], v194 offset:55296
	ds_read_b128 v[236:239], v194 offset:56320
	global_load_lds_dwordx4 v2, s[98:99]
	s_add_i32 m0, s26, 0x2000
	s_add_u32 s22, s22, 0x80080
	s_addc_u32 s23, s23, 0
	s_add_i32 s26, s49, s28
	global_load_lds_dwordx4 v156, s[98:99]
	s_mov_b32 m0, s26
	s_nop 0
	global_load_lds_dwordx4 v2, s[22:23]
	s_add_i32 m0, s26, 0x2000
	s_nop 0
	global_load_lds_dwordx4 v156, s[22:23]
	s_mov_b32 m0, s44
	s_nop 0
	global_load_lds_dwordx4 v160, s[100:101]
	s_mov_b32 m0, s45
	s_nop 0
	global_load_lds_dwordx4 v158, s[100:101]
	s_waitcnt vmcnt(8)
	s_waitcnt lgkmcnt(0)
	s_setprio 1
	s_barrier
	v_mfma_f32_16x16x32_bf16 v[80:83], v[148:151], v[204:207], v[80:83]
	v_mfma_f32_16x16x32_bf16 v[72:75], v[172:175], v[204:207], v[72:75]
	v_mfma_f32_16x16x32_bf16 v[64:67], v[148:151], v[216:219], v[64:67]
	v_mfma_f32_16x16x32_bf16 v[56:59], v[172:175], v[216:219], v[56:59]
	v_mfma_f32_16x16x32_bf16 v[48:51], v[148:151], v[224:227], v[48:51]
	v_mfma_f32_16x16x32_bf16 v[40:43], v[172:175], v[224:227], v[40:43]
	v_mfma_f32_16x16x32_bf16 v[32:35], v[148:151], v[232:235], v[32:35]
	v_mfma_f32_16x16x32_bf16 v[24:27], v[172:175], v[232:235], v[24:27]
	v_mfma_f32_16x16x32_bf16 v[80:83], v[152:155], v[212:215], v[80:83]
	v_mfma_f32_16x16x32_bf16 v[72:75], v[176:179], v[212:215], v[72:75]
	v_mfma_f32_16x16x32_bf16 v[64:67], v[152:155], v[220:223], v[64:67]
	v_mfma_f32_16x16x32_bf16 v[56:59], v[176:179], v[220:223], v[56:59]
	v_mfma_f32_16x16x32_bf16 v[48:51], v[152:155], v[228:231], v[48:51]
	v_mfma_f32_16x16x32_bf16 v[40:43], v[176:179], v[228:231], v[40:43]
	v_mfma_f32_16x16x32_bf16 v[32:35], v[152:155], v[236:239], v[32:35]
	v_mfma_f32_16x16x32_bf16 v[24:27], v[176:179], v[236:239], v[24:27]
	v_mfma_f32_16x16x32_bf16 v[76:79], v[180:183], v[204:207], v[76:79]
	v_mfma_f32_16x16x32_bf16 v[68:71], v[196:199], v[204:207], v[68:71]
	v_mfma_f32_16x16x32_bf16 v[60:63], v[180:183], v[216:219], v[60:63]
	v_mfma_f32_16x16x32_bf16 v[52:55], v[196:199], v[216:219], v[52:55]
	v_mfma_f32_16x16x32_bf16 v[44:47], v[180:183], v[224:227], v[44:47]
	v_mfma_f32_16x16x32_bf16 v[36:39], v[196:199], v[224:227], v[36:39]
	v_mfma_f32_16x16x32_bf16 v[28:31], v[180:183], v[232:235], v[28:31]
	v_mfma_f32_16x16x32_bf16 v[20:23], v[196:199], v[232:235], v[20:23]
	v_mfma_f32_16x16x32_bf16 v[76:79], v[184:187], v[212:215], v[76:79]
	v_mfma_f32_16x16x32_bf16 v[68:71], v[200:203], v[212:215], v[68:71]
	v_mfma_f32_16x16x32_bf16 v[60:63], v[184:187], v[220:223], v[60:63]
	v_mfma_f32_16x16x32_bf16 v[52:55], v[200:203], v[220:223], v[52:55]
	s_cmp_eq_u32 s35, 28
	v_mfma_f32_16x16x32_bf16 v[44:47], v[184:187], v[228:231], v[44:47]
	v_mfma_f32_16x16x32_bf16 v[36:39], v[200:203], v[228:231], v[36:39]
	s_cbranch_scc1 .Lexit_256
	v_mfma_f32_16x16x32_bf16 v[28:31], v[184:187], v[236:239], v[28:31]
	v_mfma_f32_16x16x32_bf16 v[20:23], v[200:203], v[236:239], v[20:23]
	s_barrier
	s_setprio 0
	s_add_i32 s35, s35, 2
	s_add_u32 s2, s2, 0x1000
	s_addc_u32 s3, s3, 0
	s_add_u32 s33, s33, 0x100
	s_addc_u32 s34, s34, 0
	s_cmp_gt_u32 s35, 29
	s_cbranch_scc0 .LBB0_256
.Lexit_256:
	v_mfma_f32_16x16x32_bf16 v[28:31], v[184:187], v[236:239], v[28:31]
	v_mfma_f32_16x16x32_bf16 v[20:23], v[200:203], v[236:239], v[20:23]
	s_setprio 0
	s_add_i32 s35, s35, 2
	s_add_u32 s2, s2, 0x1000
	s_addc_u32 s3, s3, 0
	s_add_u32 s33, s33, 0x100
	s_addc_u32 s34, s34, 0

.LBB0_489:
	s_add_u32 s26, s22, 0xfff80800
	s_addc_u32 s27, s23, -1
	s_add_i32 s34, 0, 0x10000
	s_cmp_eq_u32 s33, 28
	s_cselect_b32 s39, s3, s27
	s_cselect_b32 s38, s6, s26
	s_cselect_b32 s27, s8, s17
	s_cselect_b32 s26, s9, s15
	s_add_i32 s53, 0, 0x14000
	v_add_u32_e32 v144, s34, v168
	v_add_u32_e32 v160, s53, v168
	ds_read_b128 v[4:7], v144
	ds_read_b128 v[8:11], v144 offset:1024
	ds_read_b128 v[140:143], v144 offset:2048
	ds_read_b128 v[144:147], v144 offset:3072
	ds_read_b128 v[172:175], v160
	ds_read_b128 v[176:179], v160 offset:1024
	ds_read_b128 v[180:183], v160 offset:2048
	ds_read_b128 v[184:187], v160 offset:3072
	s_add_i32 m0, s13, 0xc000
	ds_read_b128 v[188:191], v170
	ds_read_b128 v[192:195], v170 offset:1024
	ds_read_b128 v[196:199], v170 offset:2048
	ds_read_b128 v[200:203], v170 offset:3072
	ds_read_b128 v[204:207], v170 offset:4096
	ds_read_b128 v[212:215], v170 offset:5120
	ds_read_b128 v[216:219], v170 offset:6144
	ds_read_b128 v[220:223], v170 offset:7168
	global_load_lds_dwordx4 v156, s[22:23]
	s_add_i32 m0, s13, 0xe000
	s_nop 0
	global_load_lds_dwordx4 v158, s[22:23]
	s_waitcnt vmcnt(8)
	s_waitcnt lgkmcnt(0)
	s_setprio 1
	s_barrier
	v_mfma_f32_16x16x32_bf16 v[136:139], v[4:7], v[188:191], v[136:139]
	v_mfma_f32_16x16x32_bf16 v[132:135], v[140:143], v[188:191], v[132:135]
	v_mfma_f32_16x16x32_bf16 v[128:131], v[4:7], v[196:199], v[128:131]
	v_mfma_f32_16x16x32_bf16 v[120:123], v[140:143], v[196:199], v[120:123]
	v_mfma_f32_16x16x32_bf16 v[112:115], v[4:7], v[204:207], v[112:115]
	v_mfma_f32_16x16x32_bf16 v[104:107], v[140:143], v[204:207], v[104:107]
	v_mfma_f32_16x16x32_bf16 v[96:99], v[4:7], v[216:219], v[96:99]
	v_mfma_f32_16x16x32_bf16 v[88:91], v[140:143], v[216:219], v[88:91]
	v_mfma_f32_16x16x32_bf16 v[136:139], v[8:11], v[192:195], v[136:139]
	v_mfma_f32_16x16x32_bf16 v[132:135], v[144:147], v[192:195], v[132:135]
	v_mfma_f32_16x16x32_bf16 v[128:131], v[8:11], v[200:203], v[128:131]
	v_mfma_f32_16x16x32_bf16 v[120:123], v[144:147], v[200:203], v[120:123]
	v_mfma_f32_16x16x32_bf16 v[112:115], v[8:11], v[212:215], v[112:115]
	v_mfma_f32_16x16x32_bf16 v[104:107], v[144:147], v[212:215], v[104:107]
	v_mfma_f32_16x16x32_bf16 v[96:99], v[8:11], v[220:223], v[96:99]
	v_mfma_f32_16x16x32_bf16 v[88:91], v[144:147], v[220:223], v[88:91]
	v_mfma_f32_16x16x32_bf16 v[124:127], v[172:175], v[188:191], v[124:127]
	v_mfma_f32_16x16x32_bf16 v[116:119], v[180:183], v[188:191], v[116:119]
	v_mfma_f32_16x16x32_bf16 v[108:111], v[172:175], v[196:199], v[108:111]
	v_mfma_f32_16x16x32_bf16 v[100:103], v[180:183], v[196:199], v[100:103]
	v_mfma_f32_16x16x32_bf16 v[92:95], v[172:175], v[204:207], v[92:95]
	v_mfma_f32_16x16x32_bf16 v[84:87], v[180:183], v[204:207], v[84:87]
	v_mfma_f32_16x16x32_bf16 v[80:83], v[172:175], v[216:219], v[80:83]
	v_mfma_f32_16x16x32_bf16 v[76:79], v[180:183], v[216:219], v[76:79]
	v_mfma_f32_16x16x32_bf16 v[124:127], v[176:179], v[192:195], v[124:127]
	v_mfma_f32_16x16x32_bf16 v[116:119], v[184:187], v[192:195], v[116:119]
	v_mfma_f32_16x16x32_bf16 v[108:111], v[176:179], v[200:203], v[108:111]
	v_mfma_f32_16x16x32_bf16 v[100:103], v[184:187], v[200:203], v[100:103]
	v_mfma_f32_16x16x32_bf16 v[92:95], v[176:179], v[212:215], v[92:95]
	v_mfma_f32_16x16x32_bf16 v[84:87], v[184:187], v[212:215], v[84:87]
	v_mfma_f32_16x16x32_bf16 v[80:83], v[176:179], v[220:223], v[80:83]
	v_mfma_f32_16x16x32_bf16 v[76:79], v[184:187], v[220:223], v[76:79]
	s_barrier
	s_setprio 0
	s_add_i32 s34, s34, s7
	s_add_u32 s98, s26, 0x80
	s_addc_u32 s99, s27, 0
	s_add_u32 s100, s38, 0x800
	s_addc_u32 s101, s39, 0
	s_mov_b32 m0, s34
	ds_read_b128 v[188:191], v170 offset:16384
	ds_read_b128 v[192:195], v170 offset:17408
	ds_read_b128 v[196:199], v170 offset:18432
	ds_read_b128 v[200:203], v170 offset:19456
	ds_read_b128 v[204:207], v170 offset:20480
	ds_read_b128 v[212:215], v170 offset:21504
	ds_read_b128 v[216:219], v170 offset:22528
	ds_read_b128 v[220:223], v170 offset:23552
	global_load_lds_dwordx4 v2, s[26:27]
	s_add_i32 m0, s34, 0x2000
	s_add_u32 s34, s26, 0x80000
	s_addc_u32 s35, s27, 0
	s_add_i32 s53, s53, s7
	global_load_lds_dwordx4 v148, s[26:27]
	s_mov_b32 m0, s53
	s_nop 0
	global_load_lds_dwordx4 v2, s[34:35]
	s_add_i32 m0, s53, 0x2000
	s_nop 0
	global_load_lds_dwordx4 v148, s[34:35]
	s_mov_b32 m0, s13
	s_nop 0
	global_load_lds_dwordx4 v152, s[38:39]
	s_mov_b32 m0, s46
	s_nop 0
	global_load_lds_dwordx4 v150, s[38:39]
	s_waitcnt vmcnt(8)
	s_waitcnt lgkmcnt(0)
	s_setprio 1
	s_barrier
	v_mfma_f32_16x16x32_bf16 v[72:75], v[4:7], v[188:191], v[72:75]
	v_mfma_f32_16x16x32_bf16 v[68:71], v[140:143], v[188:191], v[68:71]
	v_mfma_f32_16x16x32_bf16 v[64:67], v[4:7], v[196:199], v[64:67]
	v_mfma_f32_16x16x32_bf16 v[56:59], v[140:143], v[196:199], v[56:59]
	v_mfma_f32_16x16x32_bf16 v[48:51], v[4:7], v[204:207], v[48:51]
	v_mfma_f32_16x16x32_bf16 v[40:43], v[140:143], v[204:207], v[40:43]
	v_mfma_f32_16x16x32_bf16 v[4:7], v[4:7], v[216:219], v[32:35]
	v_mfma_f32_16x16x32_bf16 v[72:75], v[8:11], v[192:195], v[72:75]
	v_mfma_f32_16x16x32_bf16 v[68:71], v[144:147], v[192:195], v[68:71]
	v_mfma_f32_16x16x32_bf16 v[64:67], v[8:11], v[200:203], v[64:67]
	v_mfma_f32_16x16x32_bf16 v[56:59], v[144:147], v[200:203], v[56:59]
	v_mfma_f32_16x16x32_bf16 v[48:51], v[8:11], v[212:215], v[48:51]
	v_mfma_f32_16x16x32_bf16 v[40:43], v[144:147], v[212:215], v[40:43]
	v_mfma_f32_16x16x32_bf16 v[4:7], v[8:11], v[220:223], v[4:7]
	v_mfma_f32_16x16x32_bf16 v[8:11], v[140:143], v[216:219], v[24:27]
	v_mfma_f32_16x16x32_bf16 v[8:11], v[144:147], v[220:223], v[8:11]
	v_mfma_f32_16x16x32_bf16 v[24:27], v[172:175], v[188:191], v[60:63]
	v_mfma_f32_16x16x32_bf16 v[60:63], v[176:179], v[192:195], v[24:27]
	v_mfma_f32_16x16x32_bf16 v[24:27], v[180:183], v[188:191], v[52:55]
	v_mfma_f32_16x16x32_bf16 v[52:55], v[184:187], v[192:195], v[24:27]
	v_mfma_f32_16x16x32_bf16 v[24:27], v[172:175], v[196:199], v[44:47]
	v_mfma_f32_16x16x32_bf16 v[44:47], v[176:179], v[200:203], v[24:27]
	v_mfma_f32_16x16x32_bf16 v[24:27], v[180:183], v[196:199], v[36:39]
	v_mfma_f32_16x16x32_bf16 v[36:39], v[184:187], v[200:203], v[24:27]
	v_mfma_f32_16x16x32_bf16 v[24:27], v[172:175], v[204:207], v[28:31]
	v_mfma_f32_16x16x32_bf16 v[20:23], v[180:183], v[204:207], v[20:23]
	v_mfma_f32_16x16x32_bf16 v[16:19], v[172:175], v[216:219], v[16:19]
	v_mfma_f32_16x16x32_bf16 v[12:15], v[180:183], v[216:219], v[12:15]
	v_mfma_f32_16x16x32_bf16 v[28:31], v[176:179], v[212:215], v[24:27]
	v_mfma_f32_16x16x32_bf16 v[20:23], v[184:187], v[212:215], v[20:23]
	v_mfma_f32_16x16x32_bf16 v[16:19], v[176:179], v[220:223], v[16:19]
	v_mfma_f32_16x16x32_bf16 v[12:15], v[184:187], v[220:223], v[12:15]
	s_barrier
	s_setprio 0
	s_add_i32 s53, 0, 0x18000
	s_add_i32 s54, 0, 0x1c000
	v_add_u32_e32 v144, s53, v168
	v_add_u32_e32 v171, s54, v168
	ds_read_b128 v[24:27], v144
	ds_read_b128 v[32:35], v144 offset:1024
	ds_read_b128 v[140:143], v144 offset:2048
	ds_read_b128 v[144:147], v144 offset:3072
	ds_read_b128 v[172:175], v171
	ds_read_b128 v[176:179], v171 offset:1024
	ds_read_b128 v[180:183], v171 offset:2048
	ds_read_b128 v[184:187], v171 offset:3072
	s_add_u32 s34, s38, 0x80000
	s_addc_u32 s35, s39, 0
	s_mov_b32 m0, s47
	ds_read_b128 v[188:191], v170 offset:32768
	ds_read_b128 v[192:195], v170 offset:33792
	ds_read_b128 v[196:199], v170 offset:34816
	ds_read_b128 v[200:203], v170 offset:35840
	ds_read_b128 v[204:207], v170 offset:36864
	ds_read_b128 v[212:215], v170 offset:37888
	ds_read_b128 v[216:219], v170 offset:38912
	ds_read_b128 v[220:223], v170 offset:39936
	global_load_lds_dwordx4 v152, s[34:35]
	s_mov_b32 m0, s48
	s_nop 0
	global_load_lds_dwordx4 v150, s[34:35]
	s_waitcnt vmcnt(8)
	s_waitcnt lgkmcnt(0)
	s_setprio 1
	s_barrier
	v_mfma_f32_16x16x32_bf16 v[136:139], v[24:27], v[188:191], v[136:139]
	v_mfma_f32_16x16x32_bf16 v[132:135], v[140:143], v[188:191], v[132:135]
	v_mfma_f32_16x16x32_bf16 v[128:131], v[24:27], v[196:199], v[128:131]
	v_mfma_f32_16x16x32_bf16 v[120:123], v[140:143], v[196:199], v[120:123]
	v_mfma_f32_16x16x32_bf16 v[112:115], v[24:27], v[204:207], v[112:115]
	v_mfma_f32_16x16x32_bf16 v[104:107], v[140:143], v[204:207], v[104:107]
	v_mfma_f32_16x16x32_bf16 v[96:99], v[24:27], v[216:219], v[96:99]
	v_mfma_f32_16x16x32_bf16 v[88:91], v[140:143], v[216:219], v[88:91]
	v_mfma_f32_16x16x32_bf16 v[136:139], v[32:35], v[192:195], v[136:139]
	v_mfma_f32_16x16x32_bf16 v[132:135], v[144:147], v[192:195], v[132:135]
	v_mfma_f32_16x16x32_bf16 v[128:131], v[32:35], v[200:203], v[128:131]
	v_mfma_f32_16x16x32_bf16 v[120:123], v[144:147], v[200:203], v[120:123]
	v_mfma_f32_16x16x32_bf16 v[112:115], v[32:35], v[212:215], v[112:115]
	v_mfma_f32_16x16x32_bf16 v[104:107], v[144:147], v[212:215], v[104:107]
	v_mfma_f32_16x16x32_bf16 v[96:99], v[32:35], v[220:223], v[96:99]
	v_mfma_f32_16x16x32_bf16 v[88:91], v[144:147], v[220:223], v[88:91]
	v_mfma_f32_16x16x32_bf16 v[124:127], v[172:175], v[188:191], v[124:127]
	v_mfma_f32_16x16x32_bf16 v[116:119], v[180:183], v[188:191], v[116:119]
	v_mfma_f32_16x16x32_bf16 v[108:111], v[172:175], v[196:199], v[108:111]
	v_mfma_f32_16x16x32_bf16 v[100:103], v[180:183], v[196:199], v[100:103]
	v_mfma_f32_16x16x32_bf16 v[92:95], v[172:175], v[204:207], v[92:95]
	v_mfma_f32_16x16x32_bf16 v[84:87], v[180:183], v[204:207], v[84:87]
	v_mfma_f32_16x16x32_bf16 v[80:83], v[172:175], v[216:219], v[80:83]
	v_mfma_f32_16x16x32_bf16 v[76:79], v[180:183], v[216:219], v[76:79]
	v_mfma_f32_16x16x32_bf16 v[124:127], v[176:179], v[192:195], v[124:127]
	v_mfma_f32_16x16x32_bf16 v[116:119], v[184:187], v[192:195], v[116:119]
	v_mfma_f32_16x16x32_bf16 v[108:111], v[176:179], v[200:203], v[108:111]
	v_mfma_f32_16x16x32_bf16 v[100:103], v[184:187], v[200:203], v[100:103]
	v_mfma_f32_16x16x32_bf16 v[92:95], v[176:179], v[212:215], v[92:95]
	v_mfma_f32_16x16x32_bf16 v[84:87], v[184:187], v[212:215], v[84:87]
	v_mfma_f32_16x16x32_bf16 v[80:83], v[176:179], v[220:223], v[80:83]
	v_mfma_f32_16x16x32_bf16 v[76:79], v[184:187], v[220:223], v[76:79]
	s_barrier
	s_setprio 0
	s_add_i32 s34, s53, s7
	s_mov_b32 m0, s34
	ds_read_b128 v[188:191], v170 offset:49152
	ds_read_b128 v[192:195], v170 offset:50176
	ds_read_b128 v[196:199], v170 offset:51200
	ds_read_b128 v[200:203], v170 offset:52224
	ds_read_b128 v[204:207], v170 offset:53248
	ds_read_b128 v[212:215], v170 offset:54272
	ds_read_b128 v[216:219], v170 offset:55296
	ds_read_b128 v[220:223], v170 offset:56320
	global_load_lds_dwordx4 v2, s[98:99]
	s_add_i32 m0, s34, 0x2000
	s_add_u32 s26, s26, 0x80080
	s_addc_u32 s27, s27, 0
	s_add_i32 s34, s54, s7
	global_load_lds_dwordx4 v148, s[98:99]
	s_mov_b32 m0, s34
	s_nop 0
	global_load_lds_dwordx4 v2, s[26:27]
	s_add_i32 m0, s34, 0x2000
	s_nop 0
	global_load_lds_dwordx4 v148, s[26:27]
	s_mov_b32 m0, s49
	s_nop 0
	global_load_lds_dwordx4 v152, s[100:101]
	s_mov_b32 m0, s50
	s_nop 0
	global_load_lds_dwordx4 v150, s[100:101]
	s_waitcnt vmcnt(8)
	s_waitcnt lgkmcnt(0)
	s_setprio 1
	s_barrier
	v_mfma_f32_16x16x32_bf16 v[72:75], v[24:27], v[188:191], v[72:75]
	v_mfma_f32_16x16x32_bf16 v[64:67], v[24:27], v[196:199], v[64:67]
	v_mfma_f32_16x16x32_bf16 v[48:51], v[24:27], v[204:207], v[48:51]
	v_mfma_f32_16x16x32_bf16 v[4:7], v[24:27], v[216:219], v[4:7]
	v_mfma_f32_16x16x32_bf16 v[72:75], v[32:35], v[192:195], v[72:75]
	v_mfma_f32_16x16x32_bf16 v[68:71], v[140:143], v[188:191], v[68:71]
	v_mfma_f32_16x16x32_bf16 v[64:67], v[32:35], v[200:203], v[64:67]
	v_mfma_f32_16x16x32_bf16 v[56:59], v[140:143], v[196:199], v[56:59]
	v_mfma_f32_16x16x32_bf16 v[48:51], v[32:35], v[212:215], v[48:51]
	v_mfma_f32_16x16x32_bf16 v[40:43], v[140:143], v[204:207], v[40:43]
	v_mfma_f32_16x16x32_bf16 v[32:35], v[32:35], v[220:223], v[4:7]
	v_mfma_f32_16x16x32_bf16 v[4:7], v[140:143], v[216:219], v[8:11]
	v_mfma_f32_16x16x32_bf16 v[68:71], v[144:147], v[192:195], v[68:71]
	v_mfma_f32_16x16x32_bf16 v[56:59], v[144:147], v[200:203], v[56:59]
	v_mfma_f32_16x16x32_bf16 v[40:43], v[144:147], v[212:215], v[40:43]
	v_mfma_f32_16x16x32_bf16 v[24:27], v[144:147], v[220:223], v[4:7]
	v_mfma_f32_16x16x32_bf16 v[4:7], v[172:175], v[188:191], v[60:63]
	v_mfma_f32_16x16x32_bf16 v[60:63], v[176:179], v[192:195], v[4:7]
	v_mfma_f32_16x16x32_bf16 v[4:7], v[180:183], v[188:191], v[52:55]
	v_mfma_f32_16x16x32_bf16 v[52:55], v[184:187], v[192:195], v[4:7]
	v_mfma_f32_16x16x32_bf16 v[4:7], v[172:175], v[196:199], v[44:47]
	v_mfma_f32_16x16x32_bf16 v[44:47], v[176:179], v[200:203], v[4:7]
	v_mfma_f32_16x16x32_bf16 v[4:7], v[180:183], v[196:199], v[36:39]
	v_mfma_f32_16x16x32_bf16 v[36:39], v[184:187], v[200:203], v[4:7]
	v_mfma_f32_16x16x32_bf16 v[4:7], v[172:175], v[204:207], v[28:31]
	v_mfma_f32_16x16x32_bf16 v[28:31], v[176:179], v[212:215], v[4:7]
	v_mfma_f32_16x16x32_bf16 v[4:7], v[180:183], v[204:207], v[20:23]
	v_mfma_f32_16x16x32_bf16 v[20:23], v[184:187], v[212:215], v[4:7]
	s_cmp_eq_u32 s33, 28
	v_mfma_f32_16x16x32_bf16 v[4:7], v[172:175], v[216:219], v[16:19]
	v_mfma_f32_16x16x32_bf16 v[16:19], v[176:179], v[220:223], v[4:7]
	s_cbranch_scc1 .Lexit_489
	v_mfma_f32_16x16x32_bf16 v[4:7], v[180:183], v[216:219], v[12:15]
	v_mfma_f32_16x16x32_bf16 v[12:15], v[184:187], v[220:223], v[4:7]
	s_barrier
	s_setprio 0
	s_add_i32 s33, s33, 2
	s_add_u32 s22, s22, 0x1000
	s_addc_u32 s23, s23, 0
	s_add_u32 s15, s15, 0x100
	s_addc_u32 s17, s17, 0
	s_cmp_gt_u32 s33, 29
	s_cbranch_scc0 .LBB0_489
.Lexit_489:
	v_mfma_f32_16x16x32_bf16 v[4:7], v[180:183], v[216:219], v[12:15]
	v_mfma_f32_16x16x32_bf16 v[12:15], v[184:187], v[220:223], v[4:7]
	s_setprio 0
	s_add_i32 s33, s33, 2
	s_add_u32 s22, s22, 0x1000
	s_addc_u32 s23, s23, 0
	s_add_u32 s15, s15, 0x100
	s_addc_u32 s17, s17, 0

.LBB0_832:
	s_add_i32 s28, s9, 2
	s_add_u32 s22, s2, s100
	s_addc_u32 s23, s3, 0
	s_add_i32 s29, 0, 0x10000
	s_cmp_eq_u32 s52, s9
	s_cselect_b32 s23, s1, s23
	s_cselect_b32 s22, s0, s22
	v_add_u32_e32 v2, s29, v147
	s_cselect_b32 s35, s21, s8
	s_cselect_b32 s34, s20, s7
	s_add_i32 s9, 0, 0x14000
	ds_read_b128 v[152:155], v2
	ds_read_b128 v[156:159], v2 offset:1024
	ds_read_b128 v[160:163], v2 offset:2048
	ds_read_b128 v[168:171], v2 offset:3072
	v_add_u32_e32 v2, s9, v147
	ds_read_b128 v[172:175], v2
	ds_read_b128 v[176:179], v2 offset:1024
	ds_read_b128 v[180:183], v2 offset:2048
	ds_read_b128 v[184:187], v2 offset:3072
	s_add_i32 m0, s47, 0xc000
	ds_read_b128 v[188:191], v150
	ds_read_b128 v[192:195], v150 offset:1024
	ds_read_b128 v[196:199], v150 offset:2048
	ds_read_b128 v[200:203], v150 offset:3072
	ds_read_b128 v[204:207], v150 offset:4096
	ds_read_b128 v[210:213], v150 offset:5120
	ds_read_b128 v[214:217], v150 offset:6144
	ds_read_b128 v[218:221], v150 offset:7168
	global_load_lds_dwordx4 v140, s[2:3]
	s_add_i32 m0, s47, 0xe000
	s_nop 0
	global_load_lds_dwordx4 v142, s[2:3]
	s_waitcnt vmcnt(8)
	s_waitcnt lgkmcnt(0)
	s_setprio 1
	s_barrier
	v_mfma_f32_16x16x32_bf16 v[128:131], v[152:155], v[188:191], v[128:131]
	v_mfma_f32_16x16x32_bf16 v[124:127], v[160:163], v[188:191], v[124:127]
	v_mfma_f32_16x16x32_bf16 v[112:115], v[152:155], v[196:199], v[112:115]
	v_mfma_f32_16x16x32_bf16 v[108:111], v[160:163], v[196:199], v[108:111]
	v_mfma_f32_16x16x32_bf16 v[96:99], v[152:155], v[204:207], v[96:99]
	v_mfma_f32_16x16x32_bf16 v[92:95], v[160:163], v[204:207], v[92:95]
	v_mfma_f32_16x16x32_bf16 v[80:83], v[152:155], v[214:217], v[80:83]
	v_mfma_f32_16x16x32_bf16 v[76:79], v[160:163], v[214:217], v[76:79]
	v_mfma_f32_16x16x32_bf16 v[128:131], v[156:159], v[192:195], v[128:131]
	v_mfma_f32_16x16x32_bf16 v[124:127], v[168:171], v[192:195], v[124:127]
	v_mfma_f32_16x16x32_bf16 v[112:115], v[156:159], v[200:203], v[112:115]
	v_mfma_f32_16x16x32_bf16 v[108:111], v[168:171], v[200:203], v[108:111]
	v_mfma_f32_16x16x32_bf16 v[96:99], v[156:159], v[210:213], v[96:99]
	v_mfma_f32_16x16x32_bf16 v[92:95], v[168:171], v[210:213], v[92:95]
	v_mfma_f32_16x16x32_bf16 v[80:83], v[156:159], v[218:221], v[80:83]
	v_mfma_f32_16x16x32_bf16 v[76:79], v[168:171], v[218:221], v[76:79]
	v_mfma_f32_16x16x32_bf16 v[120:123], v[172:175], v[188:191], v[120:123]
	v_mfma_f32_16x16x32_bf16 v[116:119], v[180:183], v[188:191], v[116:119]
	v_mfma_f32_16x16x32_bf16 v[104:107], v[172:175], v[196:199], v[104:107]
	v_mfma_f32_16x16x32_bf16 v[100:103], v[180:183], v[196:199], v[100:103]
	v_mfma_f32_16x16x32_bf16 v[88:91], v[172:175], v[204:207], v[88:91]
	v_mfma_f32_16x16x32_bf16 v[84:87], v[180:183], v[204:207], v[84:87]
	v_mfma_f32_16x16x32_bf16 v[72:75], v[172:175], v[214:217], v[72:75]
	v_mfma_f32_16x16x32_bf16 v[68:71], v[180:183], v[214:217], v[68:71]
	v_mfma_f32_16x16x32_bf16 v[120:123], v[176:179], v[192:195], v[120:123]
	v_mfma_f32_16x16x32_bf16 v[116:119], v[184:187], v[192:195], v[116:119]
	v_mfma_f32_16x16x32_bf16 v[104:107], v[176:179], v[200:203], v[104:107]
	v_mfma_f32_16x16x32_bf16 v[100:103], v[184:187], v[200:203], v[100:103]
	v_mfma_f32_16x16x32_bf16 v[88:91], v[176:179], v[210:213], v[88:91]
	v_mfma_f32_16x16x32_bf16 v[84:87], v[184:187], v[210:213], v[84:87]
	v_mfma_f32_16x16x32_bf16 v[72:75], v[176:179], v[218:221], v[72:75]
	v_mfma_f32_16x16x32_bf16 v[68:71], v[184:187], v[218:221], v[68:71]
	s_barrier
	s_setprio 0
	s_add_i32 s29, s29, s26
	s_mov_b32 m0, s29
	ds_read_b128 v[188:191], v150 offset:16384
	ds_read_b128 v[192:195], v150 offset:17408
	ds_read_b128 v[196:199], v150 offset:18432
	ds_read_b128 v[200:203], v150 offset:19456
	ds_read_b128 v[204:207], v150 offset:20480
	ds_read_b128 v[210:213], v150 offset:21504
	ds_read_b128 v[214:217], v150 offset:22528
	ds_read_b128 v[218:221], v150 offset:23552
	global_load_lds_dwordx4 v136, s[34:35]
	s_add_i32 m0, s29, 0x2000
	s_add_i32 s9, s9, s26
	global_load_lds_dwordx4 v132, s[34:35]
	s_add_u32 s34, s34, s16
	s_addc_u32 s35, s35, 0
	s_mov_b32 m0, s9
	s_nop 0
	global_load_lds_dwordx4 v136, s[34:35]
	s_add_i32 m0, s9, 0x2000
	s_nop 0
	global_load_lds_dwordx4 v132, s[34:35]
	s_mov_b32 m0, s47
	s_nop 0
	global_load_lds_dwordx4 v138, s[22:23]
	s_mov_b32 m0, s48
	s_nop 0
	global_load_lds_dwordx4 v134, s[22:23]
	s_waitcnt vmcnt(8)
	s_waitcnt lgkmcnt(0)
	s_setprio 1
	s_barrier
	v_mfma_f32_16x16x32_bf16 v[64:67], v[152:155], v[188:191], v[64:67]
	v_mfma_f32_16x16x32_bf16 v[60:63], v[160:163], v[188:191], v[60:63]
	v_mfma_f32_16x16x32_bf16 v[48:51], v[152:155], v[196:199], v[48:51]
	v_mfma_f32_16x16x32_bf16 v[44:47], v[160:163], v[196:199], v[44:47]
	v_mfma_f32_16x16x32_bf16 v[32:35], v[152:155], v[204:207], v[32:35]
	v_mfma_f32_16x16x32_bf16 v[28:31], v[160:163], v[204:207], v[28:31]
	v_mfma_f32_16x16x32_bf16 v[16:19], v[152:155], v[214:217], v[16:19]
	v_mfma_f32_16x16x32_bf16 v[12:15], v[160:163], v[214:217], v[12:15]
	v_mfma_f32_16x16x32_bf16 v[64:67], v[156:159], v[192:195], v[64:67]
	v_mfma_f32_16x16x32_bf16 v[60:63], v[168:171], v[192:195], v[60:63]
	v_mfma_f32_16x16x32_bf16 v[48:51], v[156:159], v[200:203], v[48:51]
	v_mfma_f32_16x16x32_bf16 v[44:47], v[168:171], v[200:203], v[44:47]
	v_mfma_f32_16x16x32_bf16 v[32:35], v[156:159], v[210:213], v[32:35]
	v_mfma_f32_16x16x32_bf16 v[28:31], v[168:171], v[210:213], v[28:31]
	v_mfma_f32_16x16x32_bf16 v[16:19], v[156:159], v[218:221], v[16:19]
	v_mfma_f32_16x16x32_bf16 v[12:15], v[168:171], v[218:221], v[12:15]
	v_mfma_f32_16x16x32_bf16 v[56:59], v[172:175], v[188:191], v[56:59]
	v_mfma_f32_16x16x32_bf16 v[52:55], v[180:183], v[188:191], v[52:55]
	v_mfma_f32_16x16x32_bf16 v[40:43], v[172:175], v[196:199], v[40:43]
	v_mfma_f32_16x16x32_bf16 v[36:39], v[180:183], v[196:199], v[36:39]
	v_mfma_f32_16x16x32_bf16 v[24:27], v[172:175], v[204:207], v[24:27]
	v_mfma_f32_16x16x32_bf16 v[20:23], v[180:183], v[204:207], v[20:23]
	v_mfma_f32_16x16x32_bf16 v[8:11], v[172:175], v[214:217], v[8:11]
	v_mfma_f32_16x16x32_bf16 v[4:7], v[180:183], v[214:217], v[4:7]
	v_mfma_f32_16x16x32_bf16 v[56:59], v[176:179], v[192:195], v[56:59]
	v_mfma_f32_16x16x32_bf16 v[52:55], v[184:187], v[192:195], v[52:55]
	v_mfma_f32_16x16x32_bf16 v[40:43], v[176:179], v[200:203], v[40:43]
	v_mfma_f32_16x16x32_bf16 v[36:39], v[184:187], v[200:203], v[36:39]
	v_mfma_f32_16x16x32_bf16 v[24:27], v[176:179], v[210:213], v[24:27]
	v_mfma_f32_16x16x32_bf16 v[20:23], v[184:187], v[210:213], v[20:23]
	v_mfma_f32_16x16x32_bf16 v[8:11], v[176:179], v[218:221], v[8:11]
	v_mfma_f32_16x16x32_bf16 v[4:7], v[184:187], v[218:221], v[4:7]
	s_barrier
	s_setprio 0
	s_add_i32 s9, 0, 0x18000
	v_add_u32_e32 v2, s9, v147
	s_add_i32 s29, 0, 0x1c000
	ds_read_b128 v[152:155], v2
	ds_read_b128 v[156:159], v2 offset:1024
	ds_read_b128 v[160:163], v2 offset:2048
	ds_read_b128 v[168:171], v2 offset:3072
	v_add_u32_e32 v2, s29, v147
	ds_read_b128 v[172:175], v2
	ds_read_b128 v[176:179], v2 offset:1024
	ds_read_b128 v[180:183], v2 offset:2048
	ds_read_b128 v[184:187], v2 offset:3072
	s_add_u32 s22, s22, s16
	s_addc_u32 s23, s23, 0
	s_mov_b32 m0, s49
	ds_read_b128 v[188:191], v150 offset:32768
	ds_read_b128 v[192:195], v150 offset:33792
	ds_read_b128 v[196:199], v150 offset:34816
	ds_read_b128 v[200:203], v150 offset:35840
	ds_read_b128 v[204:207], v150 offset:36864
	ds_read_b128 v[210:213], v150 offset:37888
	ds_read_b128 v[214:217], v150 offset:38912
	ds_read_b128 v[218:221], v150 offset:39936
	global_load_lds_dwordx4 v138, s[22:23]
	s_mov_b32 m0, s50
	s_nop 0
	global_load_lds_dwordx4 v134, s[22:23]
	s_waitcnt vmcnt(8)
	s_waitcnt lgkmcnt(0)
	s_setprio 1
	s_barrier
	v_mfma_f32_16x16x32_bf16 v[128:131], v[152:155], v[188:191], v[128:131]
	v_mfma_f32_16x16x32_bf16 v[124:127], v[160:163], v[188:191], v[124:127]
	v_mfma_f32_16x16x32_bf16 v[112:115], v[152:155], v[196:199], v[112:115]
	v_mfma_f32_16x16x32_bf16 v[108:111], v[160:163], v[196:199], v[108:111]
	v_mfma_f32_16x16x32_bf16 v[96:99], v[152:155], v[204:207], v[96:99]
	v_mfma_f32_16x16x32_bf16 v[92:95], v[160:163], v[204:207], v[92:95]
	v_mfma_f32_16x16x32_bf16 v[80:83], v[152:155], v[214:217], v[80:83]
	v_mfma_f32_16x16x32_bf16 v[76:79], v[160:163], v[214:217], v[76:79]
	v_mfma_f32_16x16x32_bf16 v[128:131], v[156:159], v[192:195], v[128:131]
	v_mfma_f32_16x16x32_bf16 v[124:127], v[168:171], v[192:195], v[124:127]
	v_mfma_f32_16x16x32_bf16 v[112:115], v[156:159], v[200:203], v[112:115]
	v_mfma_f32_16x16x32_bf16 v[108:111], v[168:171], v[200:203], v[108:111]
	v_mfma_f32_16x16x32_bf16 v[96:99], v[156:159], v[210:213], v[96:99]
	v_mfma_f32_16x16x32_bf16 v[92:95], v[168:171], v[210:213], v[92:95]
	v_mfma_f32_16x16x32_bf16 v[80:83], v[156:159], v[218:221], v[80:83]
	v_mfma_f32_16x16x32_bf16 v[76:79], v[168:171], v[218:221], v[76:79]
	v_mfma_f32_16x16x32_bf16 v[120:123], v[172:175], v[188:191], v[120:123]
	v_mfma_f32_16x16x32_bf16 v[116:119], v[180:183], v[188:191], v[116:119]
	v_mfma_f32_16x16x32_bf16 v[104:107], v[172:175], v[196:199], v[104:107]
	v_mfma_f32_16x16x32_bf16 v[100:103], v[180:183], v[196:199], v[100:103]
	v_mfma_f32_16x16x32_bf16 v[88:91], v[172:175], v[204:207], v[88:91]
	v_mfma_f32_16x16x32_bf16 v[84:87], v[180:183], v[204:207], v[84:87]
	v_mfma_f32_16x16x32_bf16 v[72:75], v[172:175], v[214:217], v[72:75]
	v_mfma_f32_16x16x32_bf16 v[68:71], v[180:183], v[214:217], v[68:71]
	v_mfma_f32_16x16x32_bf16 v[120:123], v[176:179], v[192:195], v[120:123]
	v_mfma_f32_16x16x32_bf16 v[116:119], v[184:187], v[192:195], v[116:119]
	v_mfma_f32_16x16x32_bf16 v[104:107], v[176:179], v[200:203], v[104:107]
	v_mfma_f32_16x16x32_bf16 v[100:103], v[184:187], v[200:203], v[100:103]
	v_mfma_f32_16x16x32_bf16 v[88:91], v[176:179], v[210:213], v[88:91]
	v_mfma_f32_16x16x32_bf16 v[84:87], v[184:187], v[210:213], v[84:87]
	v_mfma_f32_16x16x32_bf16 v[72:75], v[176:179], v[218:221], v[72:75]
	v_mfma_f32_16x16x32_bf16 v[68:71], v[184:187], v[218:221], v[68:71]
	s_barrier
	s_setprio 0
	s_add_i32 s9, s9, s26
	s_mov_b32 m0, s9
	ds_read_b128 v[188:191], v150 offset:49152
	ds_read_b128 v[192:195], v150 offset:50176
	ds_read_b128 v[196:199], v150 offset:51200
	ds_read_b128 v[200:203], v150 offset:52224
	ds_read_b128 v[204:207], v150 offset:53248
	ds_read_b128 v[210:213], v150 offset:54272
	ds_read_b128 v[214:217], v150 offset:55296
	ds_read_b128 v[218:221], v150 offset:56320
	s_sub_u32 s34, s34, s16
	s_subb_u32 s35, s35, 0
	s_add_u32 s34, s34, 0x80
	s_addc_u32 s35, s35, 0
	global_load_lds_dwordx4 v136, s[34:35]
	s_add_i32 m0, s9, 0x2000
	s_add_i32 s9, s29, s26
	global_load_lds_dwordx4 v132, s[34:35]
	s_mov_b32 m0, s9
	s_nop 0
	s_add_u32 s34, s34, s16
	s_addc_u32 s35, s35, 0
	global_load_lds_dwordx4 v136, s[34:35]
	s_add_i32 m0, s9, 0x2000
	s_nop 0
	global_load_lds_dwordx4 v132, s[34:35]
	s_mov_b32 m0, s53
	s_nop 0
	s_sub_u32 s22, s22, s16
	s_subb_u32 s23, s23, 0
	s_add_u32 s22, s22, s100
	s_addc_u32 s23, s23, 0
	global_load_lds_dwordx4 v138, s[22:23]
	s_mov_b32 m0, s54
	s_nop 0
	global_load_lds_dwordx4 v134, s[22:23]
	s_waitcnt vmcnt(8)
	s_waitcnt lgkmcnt(0)
	s_setprio 1
	s_barrier
	v_mfma_f32_16x16x32_bf16 v[64:67], v[152:155], v[188:191], v[64:67]
	v_mfma_f32_16x16x32_bf16 v[60:63], v[160:163], v[188:191], v[60:63]
	v_mfma_f32_16x16x32_bf16 v[48:51], v[152:155], v[196:199], v[48:51]
	v_mfma_f32_16x16x32_bf16 v[44:47], v[160:163], v[196:199], v[44:47]
	v_mfma_f32_16x16x32_bf16 v[32:35], v[152:155], v[204:207], v[32:35]
	v_mfma_f32_16x16x32_bf16 v[28:31], v[160:163], v[204:207], v[28:31]
	v_mfma_f32_16x16x32_bf16 v[16:19], v[152:155], v[214:217], v[16:19]
	v_mfma_f32_16x16x32_bf16 v[12:15], v[160:163], v[214:217], v[12:15]
	v_mfma_f32_16x16x32_bf16 v[64:67], v[156:159], v[192:195], v[64:67]
	v_mfma_f32_16x16x32_bf16 v[60:63], v[168:171], v[192:195], v[60:63]
	v_mfma_f32_16x16x32_bf16 v[48:51], v[156:159], v[200:203], v[48:51]
	v_mfma_f32_16x16x32_bf16 v[44:47], v[168:171], v[200:203], v[44:47]
	v_mfma_f32_16x16x32_bf16 v[32:35], v[156:159], v[210:213], v[32:35]
	v_mfma_f32_16x16x32_bf16 v[28:31], v[168:171], v[210:213], v[28:31]
	v_mfma_f32_16x16x32_bf16 v[16:19], v[156:159], v[218:221], v[16:19]
	v_mfma_f32_16x16x32_bf16 v[12:15], v[168:171], v[218:221], v[12:15]
	v_mfma_f32_16x16x32_bf16 v[56:59], v[172:175], v[188:191], v[56:59]
	v_mfma_f32_16x16x32_bf16 v[52:55], v[180:183], v[188:191], v[52:55]
	v_mfma_f32_16x16x32_bf16 v[40:43], v[172:175], v[196:199], v[40:43]
	v_mfma_f32_16x16x32_bf16 v[36:39], v[180:183], v[196:199], v[36:39]
	v_mfma_f32_16x16x32_bf16 v[24:27], v[172:175], v[204:207], v[24:27]
	v_mfma_f32_16x16x32_bf16 v[20:23], v[180:183], v[204:207], v[20:23]
	v_mfma_f32_16x16x32_bf16 v[8:11], v[172:175], v[214:217], v[8:11]
	v_mfma_f32_16x16x32_bf16 v[4:7], v[180:183], v[214:217], v[4:7]
	v_mfma_f32_16x16x32_bf16 v[56:59], v[176:179], v[192:195], v[56:59]
	v_mfma_f32_16x16x32_bf16 v[52:55], v[184:187], v[192:195], v[52:55]
	v_mfma_f32_16x16x32_bf16 v[40:43], v[176:179], v[200:203], v[40:43]
	v_mfma_f32_16x16x32_bf16 v[36:39], v[184:187], v[200:203], v[36:39]
	s_cmp_ge_u32 s28, s51
	v_mfma_f32_16x16x32_bf16 v[24:27], v[176:179], v[210:213], v[24:27]
	v_mfma_f32_16x16x32_bf16 v[20:23], v[184:187], v[210:213], v[20:23]
	s_cbranch_scc1 .Lexit_832
	v_mfma_f32_16x16x32_bf16 v[8:11], v[176:179], v[218:221], v[8:11]
	v_mfma_f32_16x16x32_bf16 v[4:7], v[184:187], v[218:221], v[4:7]
	s_barrier
	s_setprio 0
	s_add_u32 s2, s2, s98
	s_addc_u32 s3, s3, 0
	s_add_u32 s7, s7, 0x100
	s_addc_u32 s8, s8, 0
	s_cmp_ge_u32 s28, s51
	s_mov_b32 s9, s28
	s_cbranch_scc0 .LBB0_832
.Lexit_832:
	v_mfma_f32_16x16x32_bf16 v[8:11], v[176:179], v[218:221], v[8:11]
	v_mfma_f32_16x16x32_bf16 v[4:7], v[184:187], v[218:221], v[4:7]
	s_setprio 0
	s_add_u32 s2, s2, s98
	s_addc_u32 s3, s3, 0
	s_add_u32 s7, s7, 0x100
	s_addc_u32 s8, s8, 0
	s_mov_b32 s9, s28
